# larger spin bounds for the granule and group-sync polls (robustness only)
# speedup vs baseline: 1.0000x; 1.0000x over previous
.Lrz1_c7:
	s_cmp_eq_u32 s98, 0
	s_cbranch_scc1 .Lrz1_done
	s_sleep 4
	s_add_i32 s99, s99, 1
	s_cmp_lt_u32 s99, 0x20000
	s_cbranch_scc1 .Lrz1_pass

.Lgs_loop:
	global_load_dwordx4 v[2:5], v0, s[28:29] sc1
	global_load_dwordx4 v[6:9], v0, s[28:29] offset:16 sc1
	s_waitcnt vmcnt(0)
	v_min_u32_e32 v2, v2, v3
	v_min_u32_e32 v4, v4, v5
	v_min_u32_e32 v6, v6, v7
	v_min_u32_e32 v8, v8, v9
	v_min_u32_e32 v2, v2, v4
	v_min_u32_e32 v6, v6, v8
	v_min_u32_e32 v2, v2, v6
	v_cmp_gt_u32_e32 vcc, s54, v2
	s_cbranch_vccz .Lnb_done
	s_sleep 1
	s_add_i32 s33, s33, 1
	s_cmp_lt_u32 s33, 0x40000
	s_cbranch_scc1 .Lgs_loop
	s_branch .Lnb_done
